# local seams 2,3,6,7 wait only for the 8 workgroups (rank mod 4) that share their row panels
# baseline (speedup 1.0000x reference)
.LBB0_262:
	s_cmp_gt_i32 s69, 3
	s_cselect_b64 s[0:1], -1, 0
	s_and_b64 s[2:3], s[4:5], s[0:1]
	s_andn2_b64 vcc, exec, s[2:3]
	s_cbranch_vccnz .LBB0_316
	s_waitcnt vmcnt(0)
	s_waitcnt vmcnt(0) lgkmcnt(0)
	s_barrier
	v_mov_b32_e32 v0, 0x20040
	ds_read_b32 v2, v0
	ds_read_b32 v3, v0 offset:16
	ds_read_b32 v5, v0 offset:8
	s_lshl_b32 s2, s33, 7
	s_add_u32 s2, s2, 0x3600
	v_lshl_add_u32 v0, v199, 2, s2
	v_mov_b32_e32 v6, 4
	v_mov_b32_e32 v7, 4
	s_waitcnt lgkmcnt(0)
	v_cmp_eq_u32_e32 vcc, 0, v3
	s_cbranch_vccnz .Lxl_orig_2
	v_cmp_lt_u32_e32 vcc, 32, v2
	s_cbranch_vccnz .Lxl_orig_2
	v_lshl_add_u32 v1, v5, 2, s2
	v_and_b32_e32 v0, 3, v5
	v_and_b32_e32 v8, 7, v199
	v_lshl_add_u32 v0, v8, 2, v0
	v_lshl_add_u32 v0, v0, 2, s2
	v_cmp_lt_u32_e32 vcc, v199, v2
	s_and_saveexec_b64 s[4:5], vcc
	s_cbranch_execz .LBB0_315
	v_cmp_eq_u32_e32 vcc, 0, v199
	s_and_saveexec_b64 s[2:3], vcc
	global_store_dword v1, v6, s[92:93]
	s_mov_b64 exec, s[2:3]
	buffer_inv sc1
	s_mov_b32 s2, 0x20000

.LBB0_363:
	s_cmp_gt_i32 s69, 4
	s_cselect_b64 s[0:1], -1, 0
	s_and_b64 s[2:3], s[8:9], s[0:1]
	s_andn2_b64 vcc, exec, s[2:3]
	s_cbranch_vccnz .LBB0_417
	s_waitcnt vmcnt(0)
	s_waitcnt vmcnt(0) lgkmcnt(0)
	s_barrier
	v_mov_b32_e32 v0, 0x20040
	ds_read_b32 v2, v0
	ds_read_b32 v3, v0 offset:16
	ds_read_b32 v5, v0 offset:8
	s_lshl_b32 s2, s33, 7
	s_add_u32 s2, s2, 0x3600
	v_lshl_add_u32 v0, v199, 2, s2
	v_mov_b32_e32 v6, 6
	v_mov_b32_e32 v7, 6
	s_waitcnt lgkmcnt(0)
	v_cmp_eq_u32_e32 vcc, 0, v3
	s_cbranch_vccnz .Lxl_orig_3
	v_cmp_lt_u32_e32 vcc, 32, v2
	s_cbranch_vccnz .Lxl_orig_3
	v_lshl_add_u32 v1, v5, 2, s2
	v_and_b32_e32 v0, 3, v5
	v_and_b32_e32 v8, 7, v199
	v_lshl_add_u32 v0, v8, 2, v0
	v_lshl_add_u32 v0, v0, 2, s2
	v_cmp_lt_u32_e32 vcc, v199, v2
	s_and_saveexec_b64 s[4:5], vcc
	s_cbranch_execz .LBB0_416
	v_cmp_eq_u32_e32 vcc, 0, v199
	s_and_saveexec_b64 s[2:3], vcc
	global_store_dword v1, v6, s[92:93]
	s_mov_b64 exec, s[2:3]
	buffer_inv sc1
	s_mov_b32 s2, 0x20000

.LBB0_1502:
	s_cmp_gt_i32 s69, 7
	s_cselect_b64 s[2:3], -1, 0
	s_and_b64 s[0:1], s[0:1], s[2:3]
	s_andn2_b64 vcc, exec, s[0:1]
	s_cbranch_vccnz .LBB0_1556
	s_waitcnt vmcnt(0)
	s_waitcnt vmcnt(0) lgkmcnt(0)
	s_barrier
	v_mov_b32_e32 v0, 0x20040
	ds_read_b32 v2, v0
	ds_read_b32 v3, v0 offset:16
	ds_read_b32 v5, v0 offset:8
	s_lshl_b32 s4, s33, 7
	s_add_u32 s4, s4, 0x3600
	v_lshl_add_u32 v0, v199, 2, s4
	v_mov_b32_e32 v6, 8
	v_mov_b32_e32 v7, 8
	s_waitcnt lgkmcnt(0)
	v_cmp_eq_u32_e32 vcc, 0, v3
	s_cbranch_vccnz .Lxl_orig_6
	v_cmp_lt_u32_e32 vcc, 32, v2
	s_cbranch_vccnz .Lxl_orig_6
	v_lshl_add_u32 v1, v5, 2, s4
	v_and_b32_e32 v0, 3, v5
	v_and_b32_e32 v8, 7, v199
	v_lshl_add_u32 v0, v8, 2, v0
	v_lshl_add_u32 v0, v0, 2, s4
	v_cmp_lt_u32_e32 vcc, v199, v2
	s_and_saveexec_b64 s[0:1], vcc
	s_cbranch_execz .LBB0_1555
	v_cmp_eq_u32_e32 vcc, 0, v199
	s_and_saveexec_b64 s[4:5], vcc
	global_store_dword v1, v6, s[92:93]
	s_mov_b64 exec, s[4:5]
	buffer_inv sc1
	s_mov_b32 s4, 0x20000

.LBB0_1599:
	s_cmp_gt_i32 s69, 8
	s_cselect_b64 s[2:3], -1, 0
	s_and_b64 s[0:1], s[0:1], s[2:3]
	v_readlane_b32 s60, v255, 20
	s_andn2_b64 vcc, exec, s[0:1]
	v_readlane_b32 s61, v255, 21
	s_cbranch_vccnz .LBB0_1653
	s_waitcnt vmcnt(0)
	s_waitcnt vmcnt(0) lgkmcnt(0)
	s_barrier
	v_mov_b32_e32 v0, 0x20040
	ds_read_b32 v2, v0
	ds_read_b32 v3, v0 offset:16
	ds_read_b32 v5, v0 offset:8
	s_lshl_b32 s4, s33, 7
	s_add_u32 s4, s4, 0x3600
	v_lshl_add_u32 v0, v199, 2, s4
	v_mov_b32_e32 v6, 10
	v_mov_b32_e32 v7, 10
	s_waitcnt lgkmcnt(0)
	v_cmp_eq_u32_e32 vcc, 0, v3
	s_cbranch_vccnz .Lxl_orig_7
	v_cmp_lt_u32_e32 vcc, 32, v2
	s_cbranch_vccnz .Lxl_orig_7
	v_lshl_add_u32 v1, v5, 2, s4
	v_and_b32_e32 v0, 3, v5
	v_and_b32_e32 v8, 7, v199
	v_lshl_add_u32 v0, v8, 2, v0
	v_lshl_add_u32 v0, v0, 2, s4
	v_cmp_lt_u32_e32 vcc, v199, v2
	s_and_saveexec_b64 s[0:1], vcc
	s_cbranch_execz .LBB0_1652
	v_cmp_eq_u32_e32 vcc, 0, v199
	s_and_saveexec_b64 s[4:5], vcc
	global_store_dword v1, v6, s[92:93]
	s_mov_b64 exec, s[4:5]
	buffer_inv sc1
	s_mov_b32 s4, 0x20000
